# hgrn pass2 state scan: loads issued 16 chunks ahead instead of one round trip per chunk
# speedup vs baseline: 1.0049x; 1.0049x over previous
; __device__ __forceinline__ unsigned cvt_pk_bf16(float lo, float hi) { const f32x2cv v = {lo, hi}; const bf16x2cv b = __builtin_convertvector(v, bf16x2cv); return __builtin_bit_cast(unsigned, b); }
; __device__ __forceinline__ float bflo(unsigned w) { return __uint_as_float(w << 16); }
; __device__ __forceinline__ float bfhi(unsigned w) { return __uint_as_float(w & 0xffff0000u); }
; __device__ __forceinline__ void hgrn_pass2(Frame& F) {
;     ...
;     for (int item = F.vcu * 256 + F.tid; item < 8 * 128 * 64; item += F.G * 256) {
;         const int bh = item >> 13, rem = item & 8191;
;         unsigned* up = (unsigned*)((bf16*)F.out + (size_t)bh * 128 * 16384) + rem; const float2* dp = (const float2*)((const float*)(F.ws + WS_HD) + (size_t)bh * 128 * 128) + (rem & 63);
;         float s0 = 0.f, s1 = 0.f;
; #pragma unroll 32
;         for (int c = 0; c < 128; ++c) { const unsigned u = up[(size_t)c * 8192]; const float2 d = dp[c * 64];
;             up[(size_t)c * 8192] = cvt_pk_bf16(s0, s1);
;             s0 = d.x * s0 + bflo(u); s1 = d.y * s1 + bfhi(u); }
.LBB0_621:
	v_ashrrev_i32_e32 v2, 13, v10
	v_and_b32_e32 v3, 0x1fff, v11
	v_lshlrev_b32_e32 v4, 22, v2
	v_lshl_or_b32 v6, v3, 2, v4
	v_lshlrev_b32_e32 v4, 16, v2
	v_add_u32_e32 v12, v4, v192
	v_add_u32_e32 v12, 0x3900000, v12
	v_mov_b32_e32 v14, v6
	v_mov_b32_e32 v8, 0
	v_mov_b32_e32 v9, 0
	global_load_dword v32, v6, s[8:9]
	global_load_dwordx2 v[64:65], v12, s[10:11]
	v_add_u32_e32 v6, 0x8000, v6
	v_add_u32_e32 v12, 0x200, v12
	global_load_dword v33, v6, s[8:9]
	global_load_dwordx2 v[66:67], v12, s[10:11]
	v_add_u32_e32 v6, 0x8000, v6
	v_add_u32_e32 v12, 0x200, v12
	global_load_dword v34, v6, s[8:9]
	global_load_dwordx2 v[68:69], v12, s[10:11]
	v_add_u32_e32 v6, 0x8000, v6
	v_add_u32_e32 v12, 0x200, v12
	global_load_dword v35, v6, s[8:9]
	global_load_dwordx2 v[70:71], v12, s[10:11]
	v_add_u32_e32 v6, 0x8000, v6
	v_add_u32_e32 v12, 0x200, v12
	global_load_dword v36, v6, s[8:9]
	global_load_dwordx2 v[72:73], v12, s[10:11]
	v_add_u32_e32 v6, 0x8000, v6
	v_add_u32_e32 v12, 0x200, v12
	global_load_dword v37, v6, s[8:9]
	global_load_dwordx2 v[74:75], v12, s[10:11]
	v_add_u32_e32 v6, 0x8000, v6
	v_add_u32_e32 v12, 0x200, v12
	global_load_dword v38, v6, s[8:9]
	global_load_dwordx2 v[76:77], v12, s[10:11]
	v_add_u32_e32 v6, 0x8000, v6
	v_add_u32_e32 v12, 0x200, v12
	global_load_dword v39, v6, s[8:9]
	global_load_dwordx2 v[78:79], v12, s[10:11]
	v_add_u32_e32 v6, 0x8000, v6
	v_add_u32_e32 v12, 0x200, v12
	global_load_dword v40, v6, s[8:9]
	global_load_dwordx2 v[80:81], v12, s[10:11]
	v_add_u32_e32 v6, 0x8000, v6
	v_add_u32_e32 v12, 0x200, v12
	global_load_dword v41, v6, s[8:9]
	global_load_dwordx2 v[82:83], v12, s[10:11]
	v_add_u32_e32 v6, 0x8000, v6
	v_add_u32_e32 v12, 0x200, v12
	global_load_dword v42, v6, s[8:9]
	global_load_dwordx2 v[84:85], v12, s[10:11]
	v_add_u32_e32 v6, 0x8000, v6
	v_add_u32_e32 v12, 0x200, v12
	global_load_dword v43, v6, s[8:9]
	global_load_dwordx2 v[86:87], v12, s[10:11]
	v_add_u32_e32 v6, 0x8000, v6
	v_add_u32_e32 v12, 0x200, v12
	global_load_dword v44, v6, s[8:9]
	global_load_dwordx2 v[88:89], v12, s[10:11]
	v_add_u32_e32 v6, 0x8000, v6
	v_add_u32_e32 v12, 0x200, v12
	global_load_dword v45, v6, s[8:9]
	global_load_dwordx2 v[90:91], v12, s[10:11]
	v_add_u32_e32 v6, 0x8000, v6
	v_add_u32_e32 v12, 0x200, v12
	global_load_dword v46, v6, s[8:9]
	global_load_dwordx2 v[92:93], v12, s[10:11]
	v_add_u32_e32 v6, 0x8000, v6
	v_add_u32_e32 v12, 0x200, v12
	global_load_dword v47, v6, s[8:9]
	global_load_dwordx2 v[94:95], v12, s[10:11]
	v_add_u32_e32 v6, 0x8000, v6
	v_add_u32_e32 v12, 0x200, v12
	s_waitcnt vmcnt(0)
	global_load_dword v48, v6, s[8:9]
	global_load_dwordx2 v[96:97], v12, s[10:11]
	v_add_u32_e32 v6, 0x8000, v6
	v_add_u32_e32 v12, 0x200, v12
	global_load_dword v49, v6, s[8:9]
	global_load_dwordx2 v[98:99], v12, s[10:11]
	v_add_u32_e32 v6, 0x8000, v6
	v_add_u32_e32 v12, 0x200, v12
	global_load_dword v50, v6, s[8:9]
	global_load_dwordx2 v[100:101], v12, s[10:11]
	v_add_u32_e32 v6, 0x8000, v6
	v_add_u32_e32 v12, 0x200, v12
	global_load_dword v51, v6, s[8:9]
	global_load_dwordx2 v[102:103], v12, s[10:11]
	v_add_u32_e32 v6, 0x8000, v6
	v_add_u32_e32 v12, 0x200, v12
	global_load_dword v52, v6, s[8:9]
	global_load_dwordx2 v[104:105], v12, s[10:11]
	v_add_u32_e32 v6, 0x8000, v6
	v_add_u32_e32 v12, 0x200, v12
	global_load_dword v53, v6, s[8:9]
	global_load_dwordx2 v[106:107], v12, s[10:11]
	v_add_u32_e32 v6, 0x8000, v6
	v_add_u32_e32 v12, 0x200, v12
	global_load_dword v54, v6, s[8:9]
	global_load_dwordx2 v[108:109], v12, s[10:11]
	v_add_u32_e32 v6, 0x8000, v6
	v_add_u32_e32 v12, 0x200, v12
	global_load_dword v55, v6, s[8:9]
	global_load_dwordx2 v[110:111], v12, s[10:11]
	v_add_u32_e32 v6, 0x8000, v6
	v_add_u32_e32 v12, 0x200, v12
	global_load_dword v56, v6, s[8:9]
	global_load_dwordx2 v[112:113], v12, s[10:11]
	v_add_u32_e32 v6, 0x8000, v6
	v_add_u32_e32 v12, 0x200, v12
	global_load_dword v57, v6, s[8:9]
	global_load_dwordx2 v[114:115], v12, s[10:11]
	v_add_u32_e32 v6, 0x8000, v6
	v_add_u32_e32 v12, 0x200, v12
	global_load_dword v58, v6, s[8:9]
	global_load_dwordx2 v[116:117], v12, s[10:11]
	v_add_u32_e32 v6, 0x8000, v6
	v_add_u32_e32 v12, 0x200, v12
	global_load_dword v59, v6, s[8:9]
	global_load_dwordx2 v[118:119], v12, s[10:11]
	v_add_u32_e32 v6, 0x8000, v6
	v_add_u32_e32 v12, 0x200, v12
	global_load_dword v60, v6, s[8:9]
	global_load_dwordx2 v[120:121], v12, s[10:11]
	v_add_u32_e32 v6, 0x8000, v6
	v_add_u32_e32 v12, 0x200, v12
	global_load_dword v61, v6, s[8:9]
	global_load_dwordx2 v[122:123], v12, s[10:11]
	v_add_u32_e32 v6, 0x8000, v6
	v_add_u32_e32 v12, 0x200, v12
	global_load_dword v62, v6, s[8:9]
	global_load_dwordx2 v[124:125], v12, s[10:11]
	v_add_u32_e32 v6, 0x8000, v6
	v_add_u32_e32 v12, 0x200, v12
	global_load_dword v63, v6, s[8:9]
	global_load_dwordx2 v[126:127], v12, s[10:11]
	v_add_u32_e32 v6, 0x8000, v6
	v_add_u32_e32 v12, 0x200, v12
	v_cvt_pk_bf16_f32 v16, v8, v9
	global_store_dword v14, v16, s[8:9]
	v_lshlrev_b32_e32 v18, 16, v32
	v_and_b32_e32 v19, 0xffff0000, v32
	v_pk_fma_f32 v[8:9], v[8:9], v[64:65], v[18:19]
	v_add_u32_e32 v14, 0x8000, v14
	v_cvt_pk_bf16_f32 v16, v8, v9
	global_store_dword v14, v16, s[8:9]
	v_lshlrev_b32_e32 v18, 16, v33
	v_and_b32_e32 v19, 0xffff0000, v33
	v_pk_fma_f32 v[8:9], v[8:9], v[66:67], v[18:19]
	v_add_u32_e32 v14, 0x8000, v14
	v_cvt_pk_bf16_f32 v16, v8, v9
	global_store_dword v14, v16, s[8:9]
	v_lshlrev_b32_e32 v18, 16, v34
	v_and_b32_e32 v19, 0xffff0000, v34
	v_pk_fma_f32 v[8:9], v[8:9], v[68:69], v[18:19]
	v_add_u32_e32 v14, 0x8000, v14
	v_cvt_pk_bf16_f32 v16, v8, v9
	global_store_dword v14, v16, s[8:9]
	v_lshlrev_b32_e32 v18, 16, v35
	v_and_b32_e32 v19, 0xffff0000, v35
; __device__ __forceinline__ unsigned cvt_pk_bf16(float lo, float hi) { const f32x2cv v = {lo, hi}; const bf16x2cv b = __builtin_convertvector(v, bf16x2cv); return __builtin_bit_cast(unsigned, b); }
; __device__ __forceinline__ float bflo(unsigned w) { return __uint_as_float(w << 16); }
; __device__ __forceinline__ float bfhi(unsigned w) { return __uint_as_float(w & 0xffff0000u); }
; __device__ __forceinline__ void hgrn_pass2(Frame& F) {
;     ...
;         for (int c = 0; c < 128; ++c) { const unsigned u = up[(size_t)c * 8192]; const float2 d = dp[c * 64];
;             up[(size_t)c * 8192] = cvt_pk_bf16(s0, s1);
;             s0 = d.x * s0 + bflo(u); s1 = d.y * s1 + bfhi(u); }
	v_pk_fma_f32 v[8:9], v[8:9], v[70:71], v[18:19]
	v_add_u32_e32 v14, 0x8000, v14
	v_cvt_pk_bf16_f32 v16, v8, v9
	global_store_dword v14, v16, s[8:9]
	v_lshlrev_b32_e32 v18, 16, v36
	v_and_b32_e32 v19, 0xffff0000, v36
	v_pk_fma_f32 v[8:9], v[8:9], v[72:73], v[18:19]
	v_add_u32_e32 v14, 0x8000, v14
	v_cvt_pk_bf16_f32 v16, v8, v9
	global_store_dword v14, v16, s[8:9]
	v_lshlrev_b32_e32 v18, 16, v37
	v_and_b32_e32 v19, 0xffff0000, v37
	v_pk_fma_f32 v[8:9], v[8:9], v[74:75], v[18:19]
	v_add_u32_e32 v14, 0x8000, v14
	v_cvt_pk_bf16_f32 v16, v8, v9
	global_store_dword v14, v16, s[8:9]
	v_lshlrev_b32_e32 v18, 16, v38
	v_and_b32_e32 v19, 0xffff0000, v38
	v_pk_fma_f32 v[8:9], v[8:9], v[76:77], v[18:19]
	v_add_u32_e32 v14, 0x8000, v14
	v_cvt_pk_bf16_f32 v16, v8, v9
	global_store_dword v14, v16, s[8:9]
	v_lshlrev_b32_e32 v18, 16, v39
	v_and_b32_e32 v19, 0xffff0000, v39
	v_pk_fma_f32 v[8:9], v[8:9], v[78:79], v[18:19]
	v_add_u32_e32 v14, 0x8000, v14
	v_cvt_pk_bf16_f32 v16, v8, v9
	global_store_dword v14, v16, s[8:9]
	v_lshlrev_b32_e32 v18, 16, v40
	v_and_b32_e32 v19, 0xffff0000, v40
	v_pk_fma_f32 v[8:9], v[8:9], v[80:81], v[18:19]
	v_add_u32_e32 v14, 0x8000, v14
	v_cvt_pk_bf16_f32 v16, v8, v9
	global_store_dword v14, v16, s[8:9]
	v_lshlrev_b32_e32 v18, 16, v41
	v_and_b32_e32 v19, 0xffff0000, v41
	v_pk_fma_f32 v[8:9], v[8:9], v[82:83], v[18:19]
	v_add_u32_e32 v14, 0x8000, v14
	v_cvt_pk_bf16_f32 v16, v8, v9
	global_store_dword v14, v16, s[8:9]
	v_lshlrev_b32_e32 v18, 16, v42
	v_and_b32_e32 v19, 0xffff0000, v42
	v_pk_fma_f32 v[8:9], v[8:9], v[84:85], v[18:19]
	v_add_u32_e32 v14, 0x8000, v14
	v_cvt_pk_bf16_f32 v16, v8, v9
	global_store_dword v14, v16, s[8:9]
	v_lshlrev_b32_e32 v18, 16, v43
	v_and_b32_e32 v19, 0xffff0000, v43
	v_pk_fma_f32 v[8:9], v[8:9], v[86:87], v[18:19]
	v_add_u32_e32 v14, 0x8000, v14
	v_cvt_pk_bf16_f32 v16, v8, v9
	global_store_dword v14, v16, s[8:9]
	v_lshlrev_b32_e32 v18, 16, v44
	v_and_b32_e32 v19, 0xffff0000, v44
	v_pk_fma_f32 v[8:9], v[8:9], v[88:89], v[18:19]
	v_add_u32_e32 v14, 0x8000, v14
	v_cvt_pk_bf16_f32 v16, v8, v9
	global_store_dword v14, v16, s[8:9]
	v_lshlrev_b32_e32 v18, 16, v45
	v_and_b32_e32 v19, 0xffff0000, v45
	v_pk_fma_f32 v[8:9], v[8:9], v[90:91], v[18:19]
	v_add_u32_e32 v14, 0x8000, v14
	v_cvt_pk_bf16_f32 v16, v8, v9
	global_store_dword v14, v16, s[8:9]
	v_lshlrev_b32_e32 v18, 16, v46
	v_and_b32_e32 v19, 0xffff0000, v46
	v_pk_fma_f32 v[8:9], v[8:9], v[92:93], v[18:19]
	v_add_u32_e32 v14, 0x8000, v14
	v_cvt_pk_bf16_f32 v16, v8, v9
	global_store_dword v14, v16, s[8:9]
	v_lshlrev_b32_e32 v18, 16, v47
	v_and_b32_e32 v19, 0xffff0000, v47
	v_pk_fma_f32 v[8:9], v[8:9], v[94:95], v[18:19]
	v_add_u32_e32 v14, 0x8000, v14
	s_waitcnt vmcnt(0)
	global_load_dword v32, v6, s[8:9]
	global_load_dwordx2 v[64:65], v12, s[10:11]
	v_add_u32_e32 v6, 0x8000, v6
	v_add_u32_e32 v12, 0x200, v12
	global_load_dword v33, v6, s[8:9]
	global_load_dwordx2 v[66:67], v12, s[10:11]
	v_add_u32_e32 v6, 0x8000, v6
	v_add_u32_e32 v12, 0x200, v12
	global_load_dword v34, v6, s[8:9]
	global_load_dwordx2 v[68:69], v12, s[10:11]
	v_add_u32_e32 v6, 0x8000, v6
	v_add_u32_e32 v12, 0x200, v12
	global_load_dword v35, v6, s[8:9]
	global_load_dwordx2 v[70:71], v12, s[10:11]
	v_add_u32_e32 v6, 0x8000, v6
	v_add_u32_e32 v12, 0x200, v12
	global_load_dword v36, v6, s[8:9]
	global_load_dwordx2 v[72:73], v12, s[10:11]
	v_add_u32_e32 v6, 0x8000, v6
	v_add_u32_e32 v12, 0x200, v12
	global_load_dword v37, v6, s[8:9]
	global_load_dwordx2 v[74:75], v12, s[10:11]
	v_add_u32_e32 v6, 0x8000, v6
	v_add_u32_e32 v12, 0x200, v12
	global_load_dword v38, v6, s[8:9]
	global_load_dwordx2 v[76:77], v12, s[10:11]
	v_add_u32_e32 v6, 0x8000, v6
	v_add_u32_e32 v12, 0x200, v12
	global_load_dword v39, v6, s[8:9]
	global_load_dwordx2 v[78:79], v12, s[10:11]
	v_add_u32_e32 v6, 0x8000, v6
	v_add_u32_e32 v12, 0x200, v12
	global_load_dword v40, v6, s[8:9]
	global_load_dwordx2 v[80:81], v12, s[10:11]
	v_add_u32_e32 v6, 0x8000, v6
	v_add_u32_e32 v12, 0x200, v12
	global_load_dword v41, v6, s[8:9]
	global_load_dwordx2 v[82:83], v12, s[10:11]
	v_add_u32_e32 v6, 0x8000, v6
	v_add_u32_e32 v12, 0x200, v12
	global_load_dword v42, v6, s[8:9]
	global_load_dwordx2 v[84:85], v12, s[10:11]
	v_add_u32_e32 v6, 0x8000, v6
	v_add_u32_e32 v12, 0x200, v12
	global_load_dword v43, v6, s[8:9]
	global_load_dwordx2 v[86:87], v12, s[10:11]
	v_add_u32_e32 v6, 0x8000, v6
	v_add_u32_e32 v12, 0x200, v12
	global_load_dword v44, v6, s[8:9]
	global_load_dwordx2 v[88:89], v12, s[10:11]
	v_add_u32_e32 v6, 0x8000, v6
	v_add_u32_e32 v12, 0x200, v12
	global_load_dword v45, v6, s[8:9]
	global_load_dwordx2 v[90:91], v12, s[10:11]
	v_add_u32_e32 v6, 0x8000, v6
	v_add_u32_e32 v12, 0x200, v12
	global_load_dword v46, v6, s[8:9]
	global_load_dwordx2 v[92:93], v12, s[10:11]
	v_add_u32_e32 v6, 0x8000, v6
	v_add_u32_e32 v12, 0x200, v12
	global_load_dword v47, v6, s[8:9]
	global_load_dwordx2 v[94:95], v12, s[10:11]
	v_add_u32_e32 v6, 0x8000, v6
	v_add_u32_e32 v12, 0x200, v12
	v_cvt_pk_bf16_f32 v16, v8, v9
	global_store_dword v14, v16, s[8:9]
	v_lshlrev_b32_e32 v18, 16, v48
	v_and_b32_e32 v19, 0xffff0000, v48
	v_pk_fma_f32 v[8:9], v[8:9], v[96:97], v[18:19]
	v_add_u32_e32 v14, 0x8000, v14
	v_cvt_pk_bf16_f32 v16, v8, v9
	global_store_dword v14, v16, s[8:9]
	v_lshlrev_b32_e32 v18, 16, v49
	v_and_b32_e32 v19, 0xffff0000, v49
	v_pk_fma_f32 v[8:9], v[8:9], v[98:99], v[18:19]
	v_add_u32_e32 v14, 0x8000, v14
	v_cvt_pk_bf16_f32 v16, v8, v9
	global_store_dword v14, v16, s[8:9]
	v_lshlrev_b32_e32 v18, 16, v50
	v_and_b32_e32 v19, 0xffff0000, v50
	v_pk_fma_f32 v[8:9], v[8:9], v[100:101], v[18:19]
	v_add_u32_e32 v14, 0x8000, v14
	v_cvt_pk_bf16_f32 v16, v8, v9
; __device__ __forceinline__ unsigned cvt_pk_bf16(float lo, float hi) { const f32x2cv v = {lo, hi}; const bf16x2cv b = __builtin_convertvector(v, bf16x2cv); return __builtin_bit_cast(unsigned, b); }
; __device__ __forceinline__ float bflo(unsigned w) { return __uint_as_float(w << 16); }
; __device__ __forceinline__ float bfhi(unsigned w) { return __uint_as_float(w & 0xffff0000u); }
; __device__ __forceinline__ void hgrn_pass2(Frame& F) {
;     ...
;         for (int c = 0; c < 128; ++c) { const unsigned u = up[(size_t)c * 8192]; const float2 d = dp[c * 64];
;             up[(size_t)c * 8192] = cvt_pk_bf16(s0, s1);
;             s0 = d.x * s0 + bflo(u); s1 = d.y * s1 + bfhi(u); }
	global_store_dword v14, v16, s[8:9]
	v_lshlrev_b32_e32 v18, 16, v51
	v_and_b32_e32 v19, 0xffff0000, v51
	v_pk_fma_f32 v[8:9], v[8:9], v[102:103], v[18:19]
	v_add_u32_e32 v14, 0x8000, v14
	v_cvt_pk_bf16_f32 v16, v8, v9
	global_store_dword v14, v16, s[8:9]
	v_lshlrev_b32_e32 v18, 16, v52
	v_and_b32_e32 v19, 0xffff0000, v52
	v_pk_fma_f32 v[8:9], v[8:9], v[104:105], v[18:19]
	v_add_u32_e32 v14, 0x8000, v14
	v_cvt_pk_bf16_f32 v16, v8, v9
	global_store_dword v14, v16, s[8:9]
	v_lshlrev_b32_e32 v18, 16, v53
	v_and_b32_e32 v19, 0xffff0000, v53
	v_pk_fma_f32 v[8:9], v[8:9], v[106:107], v[18:19]
	v_add_u32_e32 v14, 0x8000, v14
	v_cvt_pk_bf16_f32 v16, v8, v9
	global_store_dword v14, v16, s[8:9]
	v_lshlrev_b32_e32 v18, 16, v54
	v_and_b32_e32 v19, 0xffff0000, v54
	v_pk_fma_f32 v[8:9], v[8:9], v[108:109], v[18:19]
	v_add_u32_e32 v14, 0x8000, v14
	v_cvt_pk_bf16_f32 v16, v8, v9
	global_store_dword v14, v16, s[8:9]
	v_lshlrev_b32_e32 v18, 16, v55
	v_and_b32_e32 v19, 0xffff0000, v55
	v_pk_fma_f32 v[8:9], v[8:9], v[110:111], v[18:19]
	v_add_u32_e32 v14, 0x8000, v14
	v_cvt_pk_bf16_f32 v16, v8, v9
	global_store_dword v14, v16, s[8:9]
	v_lshlrev_b32_e32 v18, 16, v56
	v_and_b32_e32 v19, 0xffff0000, v56
	v_pk_fma_f32 v[8:9], v[8:9], v[112:113], v[18:19]
	v_add_u32_e32 v14, 0x8000, v14
	v_cvt_pk_bf16_f32 v16, v8, v9
	global_store_dword v14, v16, s[8:9]
	v_lshlrev_b32_e32 v18, 16, v57
	v_and_b32_e32 v19, 0xffff0000, v57
	v_pk_fma_f32 v[8:9], v[8:9], v[114:115], v[18:19]
	v_add_u32_e32 v14, 0x8000, v14
	v_cvt_pk_bf16_f32 v16, v8, v9
	global_store_dword v14, v16, s[8:9]
	v_lshlrev_b32_e32 v18, 16, v58
	v_and_b32_e32 v19, 0xffff0000, v58
	v_pk_fma_f32 v[8:9], v[8:9], v[116:117], v[18:19]
	v_add_u32_e32 v14, 0x8000, v14
	v_cvt_pk_bf16_f32 v16, v8, v9
	global_store_dword v14, v16, s[8:9]
	v_lshlrev_b32_e32 v18, 16, v59
	v_and_b32_e32 v19, 0xffff0000, v59
	v_pk_fma_f32 v[8:9], v[8:9], v[118:119], v[18:19]
	v_add_u32_e32 v14, 0x8000, v14
	v_cvt_pk_bf16_f32 v16, v8, v9
	global_store_dword v14, v16, s[8:9]
	v_lshlrev_b32_e32 v18, 16, v60
	v_and_b32_e32 v19, 0xffff0000, v60
	v_pk_fma_f32 v[8:9], v[8:9], v[120:121], v[18:19]
	v_add_u32_e32 v14, 0x8000, v14
	v_cvt_pk_bf16_f32 v16, v8, v9
	global_store_dword v14, v16, s[8:9]
	v_lshlrev_b32_e32 v18, 16, v61
	v_and_b32_e32 v19, 0xffff0000, v61
	v_pk_fma_f32 v[8:9], v[8:9], v[122:123], v[18:19]
	v_add_u32_e32 v14, 0x8000, v14
	v_cvt_pk_bf16_f32 v16, v8, v9
	global_store_dword v14, v16, s[8:9]
	v_lshlrev_b32_e32 v18, 16, v62
	v_and_b32_e32 v19, 0xffff0000, v62
	v_pk_fma_f32 v[8:9], v[8:9], v[124:125], v[18:19]
	v_add_u32_e32 v14, 0x8000, v14
	v_cvt_pk_bf16_f32 v16, v8, v9
	global_store_dword v14, v16, s[8:9]
	v_lshlrev_b32_e32 v18, 16, v63
	v_and_b32_e32 v19, 0xffff0000, v63
	v_pk_fma_f32 v[8:9], v[8:9], v[126:127], v[18:19]
	v_add_u32_e32 v14, 0x8000, v14
	s_waitcnt vmcnt(0)
	global_load_dword v48, v6, s[8:9]
	global_load_dwordx2 v[96:97], v12, s[10:11]
	v_add_u32_e32 v6, 0x8000, v6
	v_add_u32_e32 v12, 0x200, v12
	global_load_dword v49, v6, s[8:9]
	global_load_dwordx2 v[98:99], v12, s[10:11]
	v_add_u32_e32 v6, 0x8000, v6
	v_add_u32_e32 v12, 0x200, v12
	global_load_dword v50, v6, s[8:9]
	global_load_dwordx2 v[100:101], v12, s[10:11]
	v_add_u32_e32 v6, 0x8000, v6
	v_add_u32_e32 v12, 0x200, v12
	global_load_dword v51, v6, s[8:9]
	global_load_dwordx2 v[102:103], v12, s[10:11]
	v_add_u32_e32 v6, 0x8000, v6
	v_add_u32_e32 v12, 0x200, v12
	global_load_dword v52, v6, s[8:9]
	global_load_dwordx2 v[104:105], v12, s[10:11]
	v_add_u32_e32 v6, 0x8000, v6
	v_add_u32_e32 v12, 0x200, v12
	global_load_dword v53, v6, s[8:9]
	global_load_dwordx2 v[106:107], v12, s[10:11]
	v_add_u32_e32 v6, 0x8000, v6
	v_add_u32_e32 v12, 0x200, v12
	global_load_dword v54, v6, s[8:9]
	global_load_dwordx2 v[108:109], v12, s[10:11]
	v_add_u32_e32 v6, 0x8000, v6
	v_add_u32_e32 v12, 0x200, v12
	global_load_dword v55, v6, s[8:9]
	global_load_dwordx2 v[110:111], v12, s[10:11]
	v_add_u32_e32 v6, 0x8000, v6
	v_add_u32_e32 v12, 0x200, v12
	global_load_dword v56, v6, s[8:9]
	global_load_dwordx2 v[112:113], v12, s[10:11]
	v_add_u32_e32 v6, 0x8000, v6
	v_add_u32_e32 v12, 0x200, v12
	global_load_dword v57, v6, s[8:9]
	global_load_dwordx2 v[114:115], v12, s[10:11]
	v_add_u32_e32 v6, 0x8000, v6
	v_add_u32_e32 v12, 0x200, v12
	global_load_dword v58, v6, s[8:9]
	global_load_dwordx2 v[116:117], v12, s[10:11]
	v_add_u32_e32 v6, 0x8000, v6
	v_add_u32_e32 v12, 0x200, v12
	global_load_dword v59, v6, s[8:9]
	global_load_dwordx2 v[118:119], v12, s[10:11]
	v_add_u32_e32 v6, 0x8000, v6
	v_add_u32_e32 v12, 0x200, v12
	global_load_dword v60, v6, s[8:9]
	global_load_dwordx2 v[120:121], v12, s[10:11]
	v_add_u32_e32 v6, 0x8000, v6
	v_add_u32_e32 v12, 0x200, v12
	global_load_dword v61, v6, s[8:9]
	global_load_dwordx2 v[122:123], v12, s[10:11]
	v_add_u32_e32 v6, 0x8000, v6
	v_add_u32_e32 v12, 0x200, v12
	global_load_dword v62, v6, s[8:9]
	global_load_dwordx2 v[124:125], v12, s[10:11]
	v_add_u32_e32 v6, 0x8000, v6
	v_add_u32_e32 v12, 0x200, v12
	global_load_dword v63, v6, s[8:9]
	global_load_dwordx2 v[126:127], v12, s[10:11]
	v_add_u32_e32 v6, 0x8000, v6
	v_add_u32_e32 v12, 0x200, v12
	v_cvt_pk_bf16_f32 v16, v8, v9
	global_store_dword v14, v16, s[8:9]
	v_lshlrev_b32_e32 v18, 16, v32
	v_and_b32_e32 v19, 0xffff0000, v32
	v_pk_fma_f32 v[8:9], v[8:9], v[64:65], v[18:19]
	v_add_u32_e32 v14, 0x8000, v14
	v_cvt_pk_bf16_f32 v16, v8, v9
	global_store_dword v14, v16, s[8:9]
	v_lshlrev_b32_e32 v18, 16, v33
	v_and_b32_e32 v19, 0xffff0000, v33
	v_pk_fma_f32 v[8:9], v[8:9], v[66:67], v[18:19]
	v_add_u32_e32 v14, 0x8000, v14
	v_cvt_pk_bf16_f32 v16, v8, v9
	global_store_dword v14, v16, s[8:9]
	v_lshlrev_b32_e32 v18, 16, v34
; __device__ __forceinline__ unsigned cvt_pk_bf16(float lo, float hi) { const f32x2cv v = {lo, hi}; const bf16x2cv b = __builtin_convertvector(v, bf16x2cv); return __builtin_bit_cast(unsigned, b); }
; __device__ __forceinline__ float bflo(unsigned w) { return __uint_as_float(w << 16); }
; __device__ __forceinline__ float bfhi(unsigned w) { return __uint_as_float(w & 0xffff0000u); }
; __device__ __forceinline__ void hgrn_pass2(Frame& F) {
;     ...
;         for (int c = 0; c < 128; ++c) { const unsigned u = up[(size_t)c * 8192]; const float2 d = dp[c * 64];
;             up[(size_t)c * 8192] = cvt_pk_bf16(s0, s1);
;             s0 = d.x * s0 + bflo(u); s1 = d.y * s1 + bfhi(u); }
	v_and_b32_e32 v19, 0xffff0000, v34
	v_pk_fma_f32 v[8:9], v[8:9], v[68:69], v[18:19]
	v_add_u32_e32 v14, 0x8000, v14
	v_cvt_pk_bf16_f32 v16, v8, v9
	global_store_dword v14, v16, s[8:9]
	v_lshlrev_b32_e32 v18, 16, v35
	v_and_b32_e32 v19, 0xffff0000, v35
	v_pk_fma_f32 v[8:9], v[8:9], v[70:71], v[18:19]
	v_add_u32_e32 v14, 0x8000, v14
	v_cvt_pk_bf16_f32 v16, v8, v9
	global_store_dword v14, v16, s[8:9]
	v_lshlrev_b32_e32 v18, 16, v36
	v_and_b32_e32 v19, 0xffff0000, v36
	v_pk_fma_f32 v[8:9], v[8:9], v[72:73], v[18:19]
	v_add_u32_e32 v14, 0x8000, v14
	v_cvt_pk_bf16_f32 v16, v8, v9
	global_store_dword v14, v16, s[8:9]
	v_lshlrev_b32_e32 v18, 16, v37
	v_and_b32_e32 v19, 0xffff0000, v37
	v_pk_fma_f32 v[8:9], v[8:9], v[74:75], v[18:19]
	v_add_u32_e32 v14, 0x8000, v14
	v_cvt_pk_bf16_f32 v16, v8, v9
	global_store_dword v14, v16, s[8:9]
	v_lshlrev_b32_e32 v18, 16, v38
	v_and_b32_e32 v19, 0xffff0000, v38
	v_pk_fma_f32 v[8:9], v[8:9], v[76:77], v[18:19]
	v_add_u32_e32 v14, 0x8000, v14
	v_cvt_pk_bf16_f32 v16, v8, v9
	global_store_dword v14, v16, s[8:9]
	v_lshlrev_b32_e32 v18, 16, v39
	v_and_b32_e32 v19, 0xffff0000, v39
	v_pk_fma_f32 v[8:9], v[8:9], v[78:79], v[18:19]
	v_add_u32_e32 v14, 0x8000, v14
	v_cvt_pk_bf16_f32 v16, v8, v9
	global_store_dword v14, v16, s[8:9]
	v_lshlrev_b32_e32 v18, 16, v40
	v_and_b32_e32 v19, 0xffff0000, v40
	v_pk_fma_f32 v[8:9], v[8:9], v[80:81], v[18:19]
	v_add_u32_e32 v14, 0x8000, v14
	v_cvt_pk_bf16_f32 v16, v8, v9
	global_store_dword v14, v16, s[8:9]
	v_lshlrev_b32_e32 v18, 16, v41
	v_and_b32_e32 v19, 0xffff0000, v41
	v_pk_fma_f32 v[8:9], v[8:9], v[82:83], v[18:19]
	v_add_u32_e32 v14, 0x8000, v14
	v_cvt_pk_bf16_f32 v16, v8, v9
	global_store_dword v14, v16, s[8:9]
	v_lshlrev_b32_e32 v18, 16, v42
	v_and_b32_e32 v19, 0xffff0000, v42
	v_pk_fma_f32 v[8:9], v[8:9], v[84:85], v[18:19]
	v_add_u32_e32 v14, 0x8000, v14
	v_cvt_pk_bf16_f32 v16, v8, v9
	global_store_dword v14, v16, s[8:9]
	v_lshlrev_b32_e32 v18, 16, v43
	v_and_b32_e32 v19, 0xffff0000, v43
	v_pk_fma_f32 v[8:9], v[8:9], v[86:87], v[18:19]
	v_add_u32_e32 v14, 0x8000, v14
	v_cvt_pk_bf16_f32 v16, v8, v9
	global_store_dword v14, v16, s[8:9]
	v_lshlrev_b32_e32 v18, 16, v44
	v_and_b32_e32 v19, 0xffff0000, v44
	v_pk_fma_f32 v[8:9], v[8:9], v[88:89], v[18:19]
	v_add_u32_e32 v14, 0x8000, v14
	v_cvt_pk_bf16_f32 v16, v8, v9
	global_store_dword v14, v16, s[8:9]
	v_lshlrev_b32_e32 v18, 16, v45
	v_and_b32_e32 v19, 0xffff0000, v45
	v_pk_fma_f32 v[8:9], v[8:9], v[90:91], v[18:19]
	v_add_u32_e32 v14, 0x8000, v14
	v_cvt_pk_bf16_f32 v16, v8, v9
	global_store_dword v14, v16, s[8:9]
	v_lshlrev_b32_e32 v18, 16, v46
	v_and_b32_e32 v19, 0xffff0000, v46
	v_pk_fma_f32 v[8:9], v[8:9], v[92:93], v[18:19]
	v_add_u32_e32 v14, 0x8000, v14
	v_cvt_pk_bf16_f32 v16, v8, v9
	global_store_dword v14, v16, s[8:9]
	v_lshlrev_b32_e32 v18, 16, v47
	v_and_b32_e32 v19, 0xffff0000, v47
	v_pk_fma_f32 v[8:9], v[8:9], v[94:95], v[18:19]
	v_add_u32_e32 v14, 0x8000, v14
	s_waitcnt vmcnt(0)
	global_load_dword v32, v6, s[8:9]
	global_load_dwordx2 v[64:65], v12, s[10:11]
	v_add_u32_e32 v6, 0x8000, v6
	v_add_u32_e32 v12, 0x200, v12
	global_load_dword v33, v6, s[8:9]
	global_load_dwordx2 v[66:67], v12, s[10:11]
	v_add_u32_e32 v6, 0x8000, v6
	v_add_u32_e32 v12, 0x200, v12
	global_load_dword v34, v6, s[8:9]
	global_load_dwordx2 v[68:69], v12, s[10:11]
	v_add_u32_e32 v6, 0x8000, v6
	v_add_u32_e32 v12, 0x200, v12
	global_load_dword v35, v6, s[8:9]
	global_load_dwordx2 v[70:71], v12, s[10:11]
	v_add_u32_e32 v6, 0x8000, v6
	v_add_u32_e32 v12, 0x200, v12
	global_load_dword v36, v6, s[8:9]
	global_load_dwordx2 v[72:73], v12, s[10:11]
	v_add_u32_e32 v6, 0x8000, v6
	v_add_u32_e32 v12, 0x200, v12
	global_load_dword v37, v6, s[8:9]
	global_load_dwordx2 v[74:75], v12, s[10:11]
	v_add_u32_e32 v6, 0x8000, v6
	v_add_u32_e32 v12, 0x200, v12
	global_load_dword v38, v6, s[8:9]
	global_load_dwordx2 v[76:77], v12, s[10:11]
	v_add_u32_e32 v6, 0x8000, v6
	v_add_u32_e32 v12, 0x200, v12
	global_load_dword v39, v6, s[8:9]
	global_load_dwordx2 v[78:79], v12, s[10:11]
	v_add_u32_e32 v6, 0x8000, v6
	v_add_u32_e32 v12, 0x200, v12
	global_load_dword v40, v6, s[8:9]
	global_load_dwordx2 v[80:81], v12, s[10:11]
	v_add_u32_e32 v6, 0x8000, v6
	v_add_u32_e32 v12, 0x200, v12
	global_load_dword v41, v6, s[8:9]
	global_load_dwordx2 v[82:83], v12, s[10:11]
	v_add_u32_e32 v6, 0x8000, v6
	v_add_u32_e32 v12, 0x200, v12
	global_load_dword v42, v6, s[8:9]
	global_load_dwordx2 v[84:85], v12, s[10:11]
	v_add_u32_e32 v6, 0x8000, v6
	v_add_u32_e32 v12, 0x200, v12
	global_load_dword v43, v6, s[8:9]
	global_load_dwordx2 v[86:87], v12, s[10:11]
	v_add_u32_e32 v6, 0x8000, v6
	v_add_u32_e32 v12, 0x200, v12
	global_load_dword v44, v6, s[8:9]
	global_load_dwordx2 v[88:89], v12, s[10:11]
	v_add_u32_e32 v6, 0x8000, v6
	v_add_u32_e32 v12, 0x200, v12
	global_load_dword v45, v6, s[8:9]
	global_load_dwordx2 v[90:91], v12, s[10:11]
	v_add_u32_e32 v6, 0x8000, v6
	v_add_u32_e32 v12, 0x200, v12
	global_load_dword v46, v6, s[8:9]
	global_load_dwordx2 v[92:93], v12, s[10:11]
	v_add_u32_e32 v6, 0x8000, v6
	v_add_u32_e32 v12, 0x200, v12
	global_load_dword v47, v6, s[8:9]
	global_load_dwordx2 v[94:95], v12, s[10:11]
	v_add_u32_e32 v6, 0x8000, v6
	v_add_u32_e32 v12, 0x200, v12
	v_cvt_pk_bf16_f32 v16, v8, v9
	global_store_dword v14, v16, s[8:9]
	v_lshlrev_b32_e32 v18, 16, v48
	v_and_b32_e32 v19, 0xffff0000, v48
	v_pk_fma_f32 v[8:9], v[8:9], v[96:97], v[18:19]
	v_add_u32_e32 v14, 0x8000, v14
	v_cvt_pk_bf16_f32 v16, v8, v9
	global_store_dword v14, v16, s[8:9]
	v_lshlrev_b32_e32 v18, 16, v49
	v_and_b32_e32 v19, 0xffff0000, v49
	v_pk_fma_f32 v[8:9], v[8:9], v[98:99], v[18:19]
	v_add_u32_e32 v14, 0x8000, v14
; __device__ __forceinline__ unsigned cvt_pk_bf16(float lo, float hi) { const f32x2cv v = {lo, hi}; const bf16x2cv b = __builtin_convertvector(v, bf16x2cv); return __builtin_bit_cast(unsigned, b); }
; __device__ __forceinline__ float bflo(unsigned w) { return __uint_as_float(w << 16); }
; __device__ __forceinline__ float bfhi(unsigned w) { return __uint_as_float(w & 0xffff0000u); }
; __device__ __forceinline__ void hgrn_pass2(Frame& F) {
;     ...
;         for (int c = 0; c < 128; ++c) { const unsigned u = up[(size_t)c * 8192]; const float2 d = dp[c * 64];
;             up[(size_t)c * 8192] = cvt_pk_bf16(s0, s1);
;             s0 = d.x * s0 + bflo(u); s1 = d.y * s1 + bfhi(u); }
	v_cvt_pk_bf16_f32 v16, v8, v9
	global_store_dword v14, v16, s[8:9]
	v_lshlrev_b32_e32 v18, 16, v50
	v_and_b32_e32 v19, 0xffff0000, v50
	v_pk_fma_f32 v[8:9], v[8:9], v[100:101], v[18:19]
	v_add_u32_e32 v14, 0x8000, v14
	v_cvt_pk_bf16_f32 v16, v8, v9
	global_store_dword v14, v16, s[8:9]
	v_lshlrev_b32_e32 v18, 16, v51
	v_and_b32_e32 v19, 0xffff0000, v51
	v_pk_fma_f32 v[8:9], v[8:9], v[102:103], v[18:19]
	v_add_u32_e32 v14, 0x8000, v14
	v_cvt_pk_bf16_f32 v16, v8, v9
	global_store_dword v14, v16, s[8:9]
	v_lshlrev_b32_e32 v18, 16, v52
	v_and_b32_e32 v19, 0xffff0000, v52
	v_pk_fma_f32 v[8:9], v[8:9], v[104:105], v[18:19]
	v_add_u32_e32 v14, 0x8000, v14
	v_cvt_pk_bf16_f32 v16, v8, v9
	global_store_dword v14, v16, s[8:9]
	v_lshlrev_b32_e32 v18, 16, v53
	v_and_b32_e32 v19, 0xffff0000, v53
	v_pk_fma_f32 v[8:9], v[8:9], v[106:107], v[18:19]
	v_add_u32_e32 v14, 0x8000, v14
	v_cvt_pk_bf16_f32 v16, v8, v9
	global_store_dword v14, v16, s[8:9]
	v_lshlrev_b32_e32 v18, 16, v54
	v_and_b32_e32 v19, 0xffff0000, v54
	v_pk_fma_f32 v[8:9], v[8:9], v[108:109], v[18:19]
	v_add_u32_e32 v14, 0x8000, v14
	v_cvt_pk_bf16_f32 v16, v8, v9
	global_store_dword v14, v16, s[8:9]
	v_lshlrev_b32_e32 v18, 16, v55
	v_and_b32_e32 v19, 0xffff0000, v55
	v_pk_fma_f32 v[8:9], v[8:9], v[110:111], v[18:19]
	v_add_u32_e32 v14, 0x8000, v14
	v_cvt_pk_bf16_f32 v16, v8, v9
	global_store_dword v14, v16, s[8:9]
	v_lshlrev_b32_e32 v18, 16, v56
	v_and_b32_e32 v19, 0xffff0000, v56
	v_pk_fma_f32 v[8:9], v[8:9], v[112:113], v[18:19]
	v_add_u32_e32 v14, 0x8000, v14
	v_cvt_pk_bf16_f32 v16, v8, v9
	global_store_dword v14, v16, s[8:9]
	v_lshlrev_b32_e32 v18, 16, v57
	v_and_b32_e32 v19, 0xffff0000, v57
	v_pk_fma_f32 v[8:9], v[8:9], v[114:115], v[18:19]
	v_add_u32_e32 v14, 0x8000, v14
	v_cvt_pk_bf16_f32 v16, v8, v9
	global_store_dword v14, v16, s[8:9]
	v_lshlrev_b32_e32 v18, 16, v58
	v_and_b32_e32 v19, 0xffff0000, v58
	v_pk_fma_f32 v[8:9], v[8:9], v[116:117], v[18:19]
	v_add_u32_e32 v14, 0x8000, v14
	v_cvt_pk_bf16_f32 v16, v8, v9
	global_store_dword v14, v16, s[8:9]
	v_lshlrev_b32_e32 v18, 16, v59
	v_and_b32_e32 v19, 0xffff0000, v59
	v_pk_fma_f32 v[8:9], v[8:9], v[118:119], v[18:19]
	v_add_u32_e32 v14, 0x8000, v14
	v_cvt_pk_bf16_f32 v16, v8, v9
	global_store_dword v14, v16, s[8:9]
	v_lshlrev_b32_e32 v18, 16, v60
	v_and_b32_e32 v19, 0xffff0000, v60
	v_pk_fma_f32 v[8:9], v[8:9], v[120:121], v[18:19]
	v_add_u32_e32 v14, 0x8000, v14
	v_cvt_pk_bf16_f32 v16, v8, v9
	global_store_dword v14, v16, s[8:9]
	v_lshlrev_b32_e32 v18, 16, v61
	v_and_b32_e32 v19, 0xffff0000, v61
	v_pk_fma_f32 v[8:9], v[8:9], v[122:123], v[18:19]
	v_add_u32_e32 v14, 0x8000, v14
	v_cvt_pk_bf16_f32 v16, v8, v9
	global_store_dword v14, v16, s[8:9]
	v_lshlrev_b32_e32 v18, 16, v62
	v_and_b32_e32 v19, 0xffff0000, v62
	v_pk_fma_f32 v[8:9], v[8:9], v[124:125], v[18:19]
	v_add_u32_e32 v14, 0x8000, v14
	v_cvt_pk_bf16_f32 v16, v8, v9
	global_store_dword v14, v16, s[8:9]
	v_lshlrev_b32_e32 v18, 16, v63
	v_and_b32_e32 v19, 0xffff0000, v63
	v_pk_fma_f32 v[8:9], v[8:9], v[126:127], v[18:19]
	v_add_u32_e32 v14, 0x8000, v14
	s_waitcnt vmcnt(0)
	global_load_dword v48, v6, s[8:9]
	global_load_dwordx2 v[96:97], v12, s[10:11]
	v_add_u32_e32 v6, 0x8000, v6
	v_add_u32_e32 v12, 0x200, v12
	global_load_dword v49, v6, s[8:9]
	global_load_dwordx2 v[98:99], v12, s[10:11]
	v_add_u32_e32 v6, 0x8000, v6
	v_add_u32_e32 v12, 0x200, v12
	global_load_dword v50, v6, s[8:9]
	global_load_dwordx2 v[100:101], v12, s[10:11]
	v_add_u32_e32 v6, 0x8000, v6
	v_add_u32_e32 v12, 0x200, v12
	global_load_dword v51, v6, s[8:9]
	global_load_dwordx2 v[102:103], v12, s[10:11]
	v_add_u32_e32 v6, 0x8000, v6
	v_add_u32_e32 v12, 0x200, v12
	global_load_dword v52, v6, s[8:9]
	global_load_dwordx2 v[104:105], v12, s[10:11]
	v_add_u32_e32 v6, 0x8000, v6
	v_add_u32_e32 v12, 0x200, v12
	global_load_dword v53, v6, s[8:9]
	global_load_dwordx2 v[106:107], v12, s[10:11]
	v_add_u32_e32 v6, 0x8000, v6
	v_add_u32_e32 v12, 0x200, v12
	global_load_dword v54, v6, s[8:9]
	global_load_dwordx2 v[108:109], v12, s[10:11]
	v_add_u32_e32 v6, 0x8000, v6
	v_add_u32_e32 v12, 0x200, v12
	global_load_dword v55, v6, s[8:9]
	global_load_dwordx2 v[110:111], v12, s[10:11]
	v_add_u32_e32 v6, 0x8000, v6
	v_add_u32_e32 v12, 0x200, v12
	global_load_dword v56, v6, s[8:9]
	global_load_dwordx2 v[112:113], v12, s[10:11]
	v_add_u32_e32 v6, 0x8000, v6
	v_add_u32_e32 v12, 0x200, v12
	global_load_dword v57, v6, s[8:9]
	global_load_dwordx2 v[114:115], v12, s[10:11]
	v_add_u32_e32 v6, 0x8000, v6
	v_add_u32_e32 v12, 0x200, v12
	global_load_dword v58, v6, s[8:9]
	global_load_dwordx2 v[116:117], v12, s[10:11]
	v_add_u32_e32 v6, 0x8000, v6
	v_add_u32_e32 v12, 0x200, v12
	global_load_dword v59, v6, s[8:9]
	global_load_dwordx2 v[118:119], v12, s[10:11]
	v_add_u32_e32 v6, 0x8000, v6
	v_add_u32_e32 v12, 0x200, v12
	global_load_dword v60, v6, s[8:9]
	global_load_dwordx2 v[120:121], v12, s[10:11]
	v_add_u32_e32 v6, 0x8000, v6
	v_add_u32_e32 v12, 0x200, v12
	global_load_dword v61, v6, s[8:9]
	global_load_dwordx2 v[122:123], v12, s[10:11]
	v_add_u32_e32 v6, 0x8000, v6
	v_add_u32_e32 v12, 0x200, v12
	global_load_dword v62, v6, s[8:9]
	global_load_dwordx2 v[124:125], v12, s[10:11]
	v_add_u32_e32 v6, 0x8000, v6
	v_add_u32_e32 v12, 0x200, v12
	global_load_dword v63, v6, s[8:9]
	global_load_dwordx2 v[126:127], v12, s[10:11]
	v_add_u32_e32 v6, 0x8000, v6
	v_add_u32_e32 v12, 0x200, v12
	v_cvt_pk_bf16_f32 v16, v8, v9
	global_store_dword v14, v16, s[8:9]
	v_lshlrev_b32_e32 v18, 16, v32
	v_and_b32_e32 v19, 0xffff0000, v32
	v_pk_fma_f32 v[8:9], v[8:9], v[64:65], v[18:19]
	v_add_u32_e32 v14, 0x8000, v14
	v_cvt_pk_bf16_f32 v16, v8, v9
	global_store_dword v14, v16, s[8:9]
; __device__ __forceinline__ unsigned cvt_pk_bf16(float lo, float hi) { const f32x2cv v = {lo, hi}; const bf16x2cv b = __builtin_convertvector(v, bf16x2cv); return __builtin_bit_cast(unsigned, b); }
; __device__ __forceinline__ float bflo(unsigned w) { return __uint_as_float(w << 16); }
; __device__ __forceinline__ float bfhi(unsigned w) { return __uint_as_float(w & 0xffff0000u); }
; __device__ __forceinline__ void hgrn_pass2(Frame& F) {
;     ...
;         for (int c = 0; c < 128; ++c) { const unsigned u = up[(size_t)c * 8192]; const float2 d = dp[c * 64];
;             up[(size_t)c * 8192] = cvt_pk_bf16(s0, s1);
;             s0 = d.x * s0 + bflo(u); s1 = d.y * s1 + bfhi(u); }
	v_lshlrev_b32_e32 v18, 16, v33
	v_and_b32_e32 v19, 0xffff0000, v33
	v_pk_fma_f32 v[8:9], v[8:9], v[66:67], v[18:19]
	v_add_u32_e32 v14, 0x8000, v14
	v_cvt_pk_bf16_f32 v16, v8, v9
	global_store_dword v14, v16, s[8:9]
	v_lshlrev_b32_e32 v18, 16, v34
	v_and_b32_e32 v19, 0xffff0000, v34
	v_pk_fma_f32 v[8:9], v[8:9], v[68:69], v[18:19]
	v_add_u32_e32 v14, 0x8000, v14
	v_cvt_pk_bf16_f32 v16, v8, v9
	global_store_dword v14, v16, s[8:9]
	v_lshlrev_b32_e32 v18, 16, v35
	v_and_b32_e32 v19, 0xffff0000, v35
	v_pk_fma_f32 v[8:9], v[8:9], v[70:71], v[18:19]
	v_add_u32_e32 v14, 0x8000, v14
	v_cvt_pk_bf16_f32 v16, v8, v9
	global_store_dword v14, v16, s[8:9]
	v_lshlrev_b32_e32 v18, 16, v36
	v_and_b32_e32 v19, 0xffff0000, v36
	v_pk_fma_f32 v[8:9], v[8:9], v[72:73], v[18:19]
	v_add_u32_e32 v14, 0x8000, v14
	v_cvt_pk_bf16_f32 v16, v8, v9
	global_store_dword v14, v16, s[8:9]
	v_lshlrev_b32_e32 v18, 16, v37
	v_and_b32_e32 v19, 0xffff0000, v37
	v_pk_fma_f32 v[8:9], v[8:9], v[74:75], v[18:19]
	v_add_u32_e32 v14, 0x8000, v14
	v_cvt_pk_bf16_f32 v16, v8, v9
	global_store_dword v14, v16, s[8:9]
	v_lshlrev_b32_e32 v18, 16, v38
	v_and_b32_e32 v19, 0xffff0000, v38
	v_pk_fma_f32 v[8:9], v[8:9], v[76:77], v[18:19]
	v_add_u32_e32 v14, 0x8000, v14
	v_cvt_pk_bf16_f32 v16, v8, v9
	global_store_dword v14, v16, s[8:9]
	v_lshlrev_b32_e32 v18, 16, v39
	v_and_b32_e32 v19, 0xffff0000, v39
	v_pk_fma_f32 v[8:9], v[8:9], v[78:79], v[18:19]
	v_add_u32_e32 v14, 0x8000, v14
	v_cvt_pk_bf16_f32 v16, v8, v9
	global_store_dword v14, v16, s[8:9]
	v_lshlrev_b32_e32 v18, 16, v40
	v_and_b32_e32 v19, 0xffff0000, v40
	v_pk_fma_f32 v[8:9], v[8:9], v[80:81], v[18:19]
	v_add_u32_e32 v14, 0x8000, v14
	v_cvt_pk_bf16_f32 v16, v8, v9
	global_store_dword v14, v16, s[8:9]
	v_lshlrev_b32_e32 v18, 16, v41
	v_and_b32_e32 v19, 0xffff0000, v41
	v_pk_fma_f32 v[8:9], v[8:9], v[82:83], v[18:19]
	v_add_u32_e32 v14, 0x8000, v14
	v_cvt_pk_bf16_f32 v16, v8, v9
	global_store_dword v14, v16, s[8:9]
	v_lshlrev_b32_e32 v18, 16, v42
	v_and_b32_e32 v19, 0xffff0000, v42
	v_pk_fma_f32 v[8:9], v[8:9], v[84:85], v[18:19]
	v_add_u32_e32 v14, 0x8000, v14
	v_cvt_pk_bf16_f32 v16, v8, v9
	global_store_dword v14, v16, s[8:9]
	v_lshlrev_b32_e32 v18, 16, v43
	v_and_b32_e32 v19, 0xffff0000, v43
	v_pk_fma_f32 v[8:9], v[8:9], v[86:87], v[18:19]
	v_add_u32_e32 v14, 0x8000, v14
	v_cvt_pk_bf16_f32 v16, v8, v9
	global_store_dword v14, v16, s[8:9]
	v_lshlrev_b32_e32 v18, 16, v44
	v_and_b32_e32 v19, 0xffff0000, v44
	v_pk_fma_f32 v[8:9], v[8:9], v[88:89], v[18:19]
	v_add_u32_e32 v14, 0x8000, v14
	v_cvt_pk_bf16_f32 v16, v8, v9
	global_store_dword v14, v16, s[8:9]
	v_lshlrev_b32_e32 v18, 16, v45
	v_and_b32_e32 v19, 0xffff0000, v45
	v_pk_fma_f32 v[8:9], v[8:9], v[90:91], v[18:19]
	v_add_u32_e32 v14, 0x8000, v14
	v_cvt_pk_bf16_f32 v16, v8, v9
	global_store_dword v14, v16, s[8:9]
	v_lshlrev_b32_e32 v18, 16, v46
	v_and_b32_e32 v19, 0xffff0000, v46
	v_pk_fma_f32 v[8:9], v[8:9], v[92:93], v[18:19]
	v_add_u32_e32 v14, 0x8000, v14
	v_cvt_pk_bf16_f32 v16, v8, v9
	global_store_dword v14, v16, s[8:9]
	v_lshlrev_b32_e32 v18, 16, v47
	v_and_b32_e32 v19, 0xffff0000, v47
	v_pk_fma_f32 v[8:9], v[8:9], v[94:95], v[18:19]
	v_add_u32_e32 v14, 0x8000, v14
	s_waitcnt vmcnt(0)
	global_load_dword v32, v6, s[8:9]
	global_load_dwordx2 v[64:65], v12, s[10:11]
	v_add_u32_e32 v6, 0x8000, v6
	v_add_u32_e32 v12, 0x200, v12
	global_load_dword v33, v6, s[8:9]
	global_load_dwordx2 v[66:67], v12, s[10:11]
	v_add_u32_e32 v6, 0x8000, v6
	v_add_u32_e32 v12, 0x200, v12
	global_load_dword v34, v6, s[8:9]
	global_load_dwordx2 v[68:69], v12, s[10:11]
	v_add_u32_e32 v6, 0x8000, v6
	v_add_u32_e32 v12, 0x200, v12
	global_load_dword v35, v6, s[8:9]
	global_load_dwordx2 v[70:71], v12, s[10:11]
	v_add_u32_e32 v6, 0x8000, v6
	v_add_u32_e32 v12, 0x200, v12
	global_load_dword v36, v6, s[8:9]
	global_load_dwordx2 v[72:73], v12, s[10:11]
	v_add_u32_e32 v6, 0x8000, v6
	v_add_u32_e32 v12, 0x200, v12
	global_load_dword v37, v6, s[8:9]
	global_load_dwordx2 v[74:75], v12, s[10:11]
	v_add_u32_e32 v6, 0x8000, v6
	v_add_u32_e32 v12, 0x200, v12
	global_load_dword v38, v6, s[8:9]
	global_load_dwordx2 v[76:77], v12, s[10:11]
	v_add_u32_e32 v6, 0x8000, v6
	v_add_u32_e32 v12, 0x200, v12
	global_load_dword v39, v6, s[8:9]
	global_load_dwordx2 v[78:79], v12, s[10:11]
	v_add_u32_e32 v6, 0x8000, v6
	v_add_u32_e32 v12, 0x200, v12
	global_load_dword v40, v6, s[8:9]
	global_load_dwordx2 v[80:81], v12, s[10:11]
	v_add_u32_e32 v6, 0x8000, v6
	v_add_u32_e32 v12, 0x200, v12
	global_load_dword v41, v6, s[8:9]
	global_load_dwordx2 v[82:83], v12, s[10:11]
	v_add_u32_e32 v6, 0x8000, v6
	v_add_u32_e32 v12, 0x200, v12
	global_load_dword v42, v6, s[8:9]
	global_load_dwordx2 v[84:85], v12, s[10:11]
	v_add_u32_e32 v6, 0x8000, v6
	v_add_u32_e32 v12, 0x200, v12
	global_load_dword v43, v6, s[8:9]
	global_load_dwordx2 v[86:87], v12, s[10:11]
	v_add_u32_e32 v6, 0x8000, v6
	v_add_u32_e32 v12, 0x200, v12
	global_load_dword v44, v6, s[8:9]
	global_load_dwordx2 v[88:89], v12, s[10:11]
	v_add_u32_e32 v6, 0x8000, v6
	v_add_u32_e32 v12, 0x200, v12
	global_load_dword v45, v6, s[8:9]
	global_load_dwordx2 v[90:91], v12, s[10:11]
	v_add_u32_e32 v6, 0x8000, v6
	v_add_u32_e32 v12, 0x200, v12
	global_load_dword v46, v6, s[8:9]
	global_load_dwordx2 v[92:93], v12, s[10:11]
	v_add_u32_e32 v6, 0x8000, v6
	v_add_u32_e32 v12, 0x200, v12
	global_load_dword v47, v6, s[8:9]
	global_load_dwordx2 v[94:95], v12, s[10:11]
	v_add_u32_e32 v6, 0x8000, v6
	v_add_u32_e32 v12, 0x200, v12
	v_cvt_pk_bf16_f32 v16, v8, v9
	global_store_dword v14, v16, s[8:9]
	v_lshlrev_b32_e32 v18, 16, v48
	v_and_b32_e32 v19, 0xffff0000, v48
	v_pk_fma_f32 v[8:9], v[8:9], v[96:97], v[18:19]
; __device__ __forceinline__ unsigned cvt_pk_bf16(float lo, float hi) { const f32x2cv v = {lo, hi}; const bf16x2cv b = __builtin_convertvector(v, bf16x2cv); return __builtin_bit_cast(unsigned, b); }
; __device__ __forceinline__ float bflo(unsigned w) { return __uint_as_float(w << 16); }
; __device__ __forceinline__ float bfhi(unsigned w) { return __uint_as_float(w & 0xffff0000u); }
; __device__ __forceinline__ void hgrn_pass2(Frame& F) {
;     ...
;         for (int c = 0; c < 128; ++c) { const unsigned u = up[(size_t)c * 8192]; const float2 d = dp[c * 64];
;             up[(size_t)c * 8192] = cvt_pk_bf16(s0, s1);
;             s0 = d.x * s0 + bflo(u); s1 = d.y * s1 + bfhi(u); }
	v_add_u32_e32 v14, 0x8000, v14
	v_cvt_pk_bf16_f32 v16, v8, v9
	global_store_dword v14, v16, s[8:9]
	v_lshlrev_b32_e32 v18, 16, v49
	v_and_b32_e32 v19, 0xffff0000, v49
	v_pk_fma_f32 v[8:9], v[8:9], v[98:99], v[18:19]
	v_add_u32_e32 v14, 0x8000, v14
	v_cvt_pk_bf16_f32 v16, v8, v9
	global_store_dword v14, v16, s[8:9]
	v_lshlrev_b32_e32 v18, 16, v50
	v_and_b32_e32 v19, 0xffff0000, v50
	v_pk_fma_f32 v[8:9], v[8:9], v[100:101], v[18:19]
	v_add_u32_e32 v14, 0x8000, v14
	v_cvt_pk_bf16_f32 v16, v8, v9
	global_store_dword v14, v16, s[8:9]
	v_lshlrev_b32_e32 v18, 16, v51
	v_and_b32_e32 v19, 0xffff0000, v51
	v_pk_fma_f32 v[8:9], v[8:9], v[102:103], v[18:19]
	v_add_u32_e32 v14, 0x8000, v14
	v_cvt_pk_bf16_f32 v16, v8, v9
	global_store_dword v14, v16, s[8:9]
	v_lshlrev_b32_e32 v18, 16, v52
	v_and_b32_e32 v19, 0xffff0000, v52
	v_pk_fma_f32 v[8:9], v[8:9], v[104:105], v[18:19]
	v_add_u32_e32 v14, 0x8000, v14
	v_cvt_pk_bf16_f32 v16, v8, v9
	global_store_dword v14, v16, s[8:9]
	v_lshlrev_b32_e32 v18, 16, v53
	v_and_b32_e32 v19, 0xffff0000, v53
	v_pk_fma_f32 v[8:9], v[8:9], v[106:107], v[18:19]
	v_add_u32_e32 v14, 0x8000, v14
	v_cvt_pk_bf16_f32 v16, v8, v9
	global_store_dword v14, v16, s[8:9]
	v_lshlrev_b32_e32 v18, 16, v54
	v_and_b32_e32 v19, 0xffff0000, v54
	v_pk_fma_f32 v[8:9], v[8:9], v[108:109], v[18:19]
	v_add_u32_e32 v14, 0x8000, v14
	v_cvt_pk_bf16_f32 v16, v8, v9
	global_store_dword v14, v16, s[8:9]
	v_lshlrev_b32_e32 v18, 16, v55
	v_and_b32_e32 v19, 0xffff0000, v55
	v_pk_fma_f32 v[8:9], v[8:9], v[110:111], v[18:19]
	v_add_u32_e32 v14, 0x8000, v14
	v_cvt_pk_bf16_f32 v16, v8, v9
	global_store_dword v14, v16, s[8:9]
	v_lshlrev_b32_e32 v18, 16, v56
	v_and_b32_e32 v19, 0xffff0000, v56
	v_pk_fma_f32 v[8:9], v[8:9], v[112:113], v[18:19]
	v_add_u32_e32 v14, 0x8000, v14
	v_cvt_pk_bf16_f32 v16, v8, v9
	global_store_dword v14, v16, s[8:9]
	v_lshlrev_b32_e32 v18, 16, v57
	v_and_b32_e32 v19, 0xffff0000, v57
	v_pk_fma_f32 v[8:9], v[8:9], v[114:115], v[18:19]
	v_add_u32_e32 v14, 0x8000, v14
	v_cvt_pk_bf16_f32 v16, v8, v9
	global_store_dword v14, v16, s[8:9]
	v_lshlrev_b32_e32 v18, 16, v58
	v_and_b32_e32 v19, 0xffff0000, v58
	v_pk_fma_f32 v[8:9], v[8:9], v[116:117], v[18:19]
	v_add_u32_e32 v14, 0x8000, v14
	v_cvt_pk_bf16_f32 v16, v8, v9
	global_store_dword v14, v16, s[8:9]
	v_lshlrev_b32_e32 v18, 16, v59
	v_and_b32_e32 v19, 0xffff0000, v59
	v_pk_fma_f32 v[8:9], v[8:9], v[118:119], v[18:19]
	v_add_u32_e32 v14, 0x8000, v14
	v_cvt_pk_bf16_f32 v16, v8, v9
	global_store_dword v14, v16, s[8:9]
	v_lshlrev_b32_e32 v18, 16, v60
	v_and_b32_e32 v19, 0xffff0000, v60
	v_pk_fma_f32 v[8:9], v[8:9], v[120:121], v[18:19]
	v_add_u32_e32 v14, 0x8000, v14
	v_cvt_pk_bf16_f32 v16, v8, v9
	global_store_dword v14, v16, s[8:9]
	v_lshlrev_b32_e32 v18, 16, v61
	v_and_b32_e32 v19, 0xffff0000, v61
	v_pk_fma_f32 v[8:9], v[8:9], v[122:123], v[18:19]
	v_add_u32_e32 v14, 0x8000, v14
	v_cvt_pk_bf16_f32 v16, v8, v9
	global_store_dword v14, v16, s[8:9]
	v_lshlrev_b32_e32 v18, 16, v62
	v_and_b32_e32 v19, 0xffff0000, v62
	v_pk_fma_f32 v[8:9], v[8:9], v[124:125], v[18:19]
	v_add_u32_e32 v14, 0x8000, v14
	v_cvt_pk_bf16_f32 v16, v8, v9
	global_store_dword v14, v16, s[8:9]
	v_lshlrev_b32_e32 v18, 16, v63
	v_and_b32_e32 v19, 0xffff0000, v63
	v_pk_fma_f32 v[8:9], v[8:9], v[126:127], v[18:19]
	v_add_u32_e32 v14, 0x8000, v14
	s_waitcnt vmcnt(0)
	global_load_dword v48, v6, s[8:9]
	global_load_dwordx2 v[96:97], v12, s[10:11]
	v_add_u32_e32 v6, 0x8000, v6
	v_add_u32_e32 v12, 0x200, v12
	global_load_dword v49, v6, s[8:9]
	global_load_dwordx2 v[98:99], v12, s[10:11]
	v_add_u32_e32 v6, 0x8000, v6
	v_add_u32_e32 v12, 0x200, v12
	global_load_dword v50, v6, s[8:9]
	global_load_dwordx2 v[100:101], v12, s[10:11]
	v_add_u32_e32 v6, 0x8000, v6
	v_add_u32_e32 v12, 0x200, v12
	global_load_dword v51, v6, s[8:9]
	global_load_dwordx2 v[102:103], v12, s[10:11]
	v_add_u32_e32 v6, 0x8000, v6
	v_add_u32_e32 v12, 0x200, v12
	global_load_dword v52, v6, s[8:9]
	global_load_dwordx2 v[104:105], v12, s[10:11]
	v_add_u32_e32 v6, 0x8000, v6
	v_add_u32_e32 v12, 0x200, v12
	global_load_dword v53, v6, s[8:9]
	global_load_dwordx2 v[106:107], v12, s[10:11]
	v_add_u32_e32 v6, 0x8000, v6
	v_add_u32_e32 v12, 0x200, v12
	global_load_dword v54, v6, s[8:9]
	global_load_dwordx2 v[108:109], v12, s[10:11]
	v_add_u32_e32 v6, 0x8000, v6
	v_add_u32_e32 v12, 0x200, v12
	global_load_dword v55, v6, s[8:9]
	global_load_dwordx2 v[110:111], v12, s[10:11]
	v_add_u32_e32 v6, 0x8000, v6
	v_add_u32_e32 v12, 0x200, v12
	global_load_dword v56, v6, s[8:9]
	global_load_dwordx2 v[112:113], v12, s[10:11]
	v_add_u32_e32 v6, 0x8000, v6
	v_add_u32_e32 v12, 0x200, v12
	global_load_dword v57, v6, s[8:9]
	global_load_dwordx2 v[114:115], v12, s[10:11]
	v_add_u32_e32 v6, 0x8000, v6
	v_add_u32_e32 v12, 0x200, v12
	global_load_dword v58, v6, s[8:9]
	global_load_dwordx2 v[116:117], v12, s[10:11]
	v_add_u32_e32 v6, 0x8000, v6
	v_add_u32_e32 v12, 0x200, v12
	global_load_dword v59, v6, s[8:9]
	global_load_dwordx2 v[118:119], v12, s[10:11]
	v_add_u32_e32 v6, 0x8000, v6
	v_add_u32_e32 v12, 0x200, v12
	global_load_dword v60, v6, s[8:9]
	global_load_dwordx2 v[120:121], v12, s[10:11]
	v_add_u32_e32 v6, 0x8000, v6
	v_add_u32_e32 v12, 0x200, v12
	global_load_dword v61, v6, s[8:9]
	global_load_dwordx2 v[122:123], v12, s[10:11]
	v_add_u32_e32 v6, 0x8000, v6
	v_add_u32_e32 v12, 0x200, v12
	global_load_dword v62, v6, s[8:9]
	global_load_dwordx2 v[124:125], v12, s[10:11]
	v_add_u32_e32 v6, 0x8000, v6
	v_add_u32_e32 v12, 0x200, v12
	global_load_dword v63, v6, s[8:9]
	global_load_dwordx2 v[126:127], v12, s[10:11]
	v_add_u32_e32 v6, 0x8000, v6
	v_add_u32_e32 v12, 0x200, v12
	v_cvt_pk_bf16_f32 v16, v8, v9
; __device__ __forceinline__ unsigned cvt_pk_bf16(float lo, float hi) { const f32x2cv v = {lo, hi}; const bf16x2cv b = __builtin_convertvector(v, bf16x2cv); return __builtin_bit_cast(unsigned, b); }
; __device__ __forceinline__ float bflo(unsigned w) { return __uint_as_float(w << 16); }
; __device__ __forceinline__ float bfhi(unsigned w) { return __uint_as_float(w & 0xffff0000u); }
; __device__ __forceinline__ void hgrn_pass2(Frame& F) {
;     ...
;         for (int c = 0; c < 128; ++c) { const unsigned u = up[(size_t)c * 8192]; const float2 d = dp[c * 64];
;             up[(size_t)c * 8192] = cvt_pk_bf16(s0, s1);
;             s0 = d.x * s0 + bflo(u); s1 = d.y * s1 + bfhi(u); }
	global_store_dword v14, v16, s[8:9]
	v_lshlrev_b32_e32 v18, 16, v32
	v_and_b32_e32 v19, 0xffff0000, v32
	v_pk_fma_f32 v[8:9], v[8:9], v[64:65], v[18:19]
	v_add_u32_e32 v14, 0x8000, v14
	v_cvt_pk_bf16_f32 v16, v8, v9
	global_store_dword v14, v16, s[8:9]
	v_lshlrev_b32_e32 v18, 16, v33
	v_and_b32_e32 v19, 0xffff0000, v33
	v_pk_fma_f32 v[8:9], v[8:9], v[66:67], v[18:19]
	v_add_u32_e32 v14, 0x8000, v14
	v_cvt_pk_bf16_f32 v16, v8, v9
	global_store_dword v14, v16, s[8:9]
	v_lshlrev_b32_e32 v18, 16, v34
	v_and_b32_e32 v19, 0xffff0000, v34
	v_pk_fma_f32 v[8:9], v[8:9], v[68:69], v[18:19]
	v_add_u32_e32 v14, 0x8000, v14
	v_cvt_pk_bf16_f32 v16, v8, v9
	global_store_dword v14, v16, s[8:9]
	v_lshlrev_b32_e32 v18, 16, v35
	v_and_b32_e32 v19, 0xffff0000, v35
	v_pk_fma_f32 v[8:9], v[8:9], v[70:71], v[18:19]
	v_add_u32_e32 v14, 0x8000, v14
	v_cvt_pk_bf16_f32 v16, v8, v9
	global_store_dword v14, v16, s[8:9]
	v_lshlrev_b32_e32 v18, 16, v36
	v_and_b32_e32 v19, 0xffff0000, v36
	v_pk_fma_f32 v[8:9], v[8:9], v[72:73], v[18:19]
	v_add_u32_e32 v14, 0x8000, v14
	v_cvt_pk_bf16_f32 v16, v8, v9
	global_store_dword v14, v16, s[8:9]
	v_lshlrev_b32_e32 v18, 16, v37
	v_and_b32_e32 v19, 0xffff0000, v37
	v_pk_fma_f32 v[8:9], v[8:9], v[74:75], v[18:19]
	v_add_u32_e32 v14, 0x8000, v14
	v_cvt_pk_bf16_f32 v16, v8, v9
	global_store_dword v14, v16, s[8:9]
	v_lshlrev_b32_e32 v18, 16, v38
	v_and_b32_e32 v19, 0xffff0000, v38
	v_pk_fma_f32 v[8:9], v[8:9], v[76:77], v[18:19]
	v_add_u32_e32 v14, 0x8000, v14
	v_cvt_pk_bf16_f32 v16, v8, v9
	global_store_dword v14, v16, s[8:9]
	v_lshlrev_b32_e32 v18, 16, v39
	v_and_b32_e32 v19, 0xffff0000, v39
	v_pk_fma_f32 v[8:9], v[8:9], v[78:79], v[18:19]
	v_add_u32_e32 v14, 0x8000, v14
	v_cvt_pk_bf16_f32 v16, v8, v9
	global_store_dword v14, v16, s[8:9]
	v_lshlrev_b32_e32 v18, 16, v40
	v_and_b32_e32 v19, 0xffff0000, v40
	v_pk_fma_f32 v[8:9], v[8:9], v[80:81], v[18:19]
	v_add_u32_e32 v14, 0x8000, v14
	v_cvt_pk_bf16_f32 v16, v8, v9
	global_store_dword v14, v16, s[8:9]
	v_lshlrev_b32_e32 v18, 16, v41
	v_and_b32_e32 v19, 0xffff0000, v41
	v_pk_fma_f32 v[8:9], v[8:9], v[82:83], v[18:19]
	v_add_u32_e32 v14, 0x8000, v14
	v_cvt_pk_bf16_f32 v16, v8, v9
	global_store_dword v14, v16, s[8:9]
	v_lshlrev_b32_e32 v18, 16, v42
	v_and_b32_e32 v19, 0xffff0000, v42
	v_pk_fma_f32 v[8:9], v[8:9], v[84:85], v[18:19]
	v_add_u32_e32 v14, 0x8000, v14
	v_cvt_pk_bf16_f32 v16, v8, v9
	global_store_dword v14, v16, s[8:9]
	v_lshlrev_b32_e32 v18, 16, v43
	v_and_b32_e32 v19, 0xffff0000, v43
	v_pk_fma_f32 v[8:9], v[8:9], v[86:87], v[18:19]
	v_add_u32_e32 v14, 0x8000, v14
	v_cvt_pk_bf16_f32 v16, v8, v9
	global_store_dword v14, v16, s[8:9]
	v_lshlrev_b32_e32 v18, 16, v44
	v_and_b32_e32 v19, 0xffff0000, v44
	v_pk_fma_f32 v[8:9], v[8:9], v[88:89], v[18:19]
	v_add_u32_e32 v14, 0x8000, v14
	v_cvt_pk_bf16_f32 v16, v8, v9
	global_store_dword v14, v16, s[8:9]
	v_lshlrev_b32_e32 v18, 16, v45
	v_and_b32_e32 v19, 0xffff0000, v45
	v_pk_fma_f32 v[8:9], v[8:9], v[90:91], v[18:19]
	v_add_u32_e32 v14, 0x8000, v14
	v_cvt_pk_bf16_f32 v16, v8, v9
	global_store_dword v14, v16, s[8:9]
	v_lshlrev_b32_e32 v18, 16, v46
	v_and_b32_e32 v19, 0xffff0000, v46
	v_pk_fma_f32 v[8:9], v[8:9], v[92:93], v[18:19]
	v_add_u32_e32 v14, 0x8000, v14
	v_cvt_pk_bf16_f32 v16, v8, v9
	global_store_dword v14, v16, s[8:9]
	v_lshlrev_b32_e32 v18, 16, v47
	v_and_b32_e32 v19, 0xffff0000, v47
	v_pk_fma_f32 v[8:9], v[8:9], v[94:95], v[18:19]
	v_add_u32_e32 v14, 0x8000, v14
	s_waitcnt vmcnt(0)
; __device__ __forceinline__ unsigned cvt_pk_bf16(float lo, float hi) { const f32x2cv v = {lo, hi}; const bf16x2cv b = __builtin_convertvector(v, bf16x2cv); return __builtin_bit_cast(unsigned, b); }
; __device__ __forceinline__ float bflo(unsigned w) { return __uint_as_float(w << 16); }
; __device__ __forceinline__ float bfhi(unsigned w) { return __uint_as_float(w & 0xffff0000u); }
; __device__ __forceinline__ void hgrn_pass2(Frame& F) {
;     ...
;     for (int item = F.vcu * 256 + F.tid; item < 8 * 128 * 64; item += F.G * 256) {
;         const int bh = item >> 13, rem = item & 8191;
;         unsigned* up = (unsigned*)((bf16*)F.out + (size_t)bh * 128 * 16384) + rem; const float2* dp = (const float2*)((const float*)(F.ws + WS_HD) + (size_t)bh * 128 * 128) + (rem & 63);
;         float s0 = 0.f, s1 = 0.f;
; #pragma unroll 32
;         for (int c = 0; c < 128; ++c) { const unsigned u = up[(size_t)c * 8192]; const float2 d = dp[c * 64];
;             up[(size_t)c * 8192] = cvt_pk_bf16(s0, s1);
;             s0 = d.x * s0 + bflo(u); s1 = d.y * s1 + bfhi(u); }
	v_cvt_pk_bf16_f32 v16, v8, v9
	global_store_dword v14, v16, s[8:9]
	v_lshlrev_b32_e32 v18, 16, v48
	v_and_b32_e32 v19, 0xffff0000, v48
	v_pk_fma_f32 v[8:9], v[8:9], v[96:97], v[18:19]
	v_add_u32_e32 v14, 0x8000, v14
	v_cvt_pk_bf16_f32 v16, v8, v9
	global_store_dword v14, v16, s[8:9]
	v_lshlrev_b32_e32 v18, 16, v49
	v_and_b32_e32 v19, 0xffff0000, v49
	v_pk_fma_f32 v[8:9], v[8:9], v[98:99], v[18:19]
	v_add_u32_e32 v14, 0x8000, v14
	v_cvt_pk_bf16_f32 v16, v8, v9
	global_store_dword v14, v16, s[8:9]
	v_lshlrev_b32_e32 v18, 16, v50
	v_and_b32_e32 v19, 0xffff0000, v50
	v_pk_fma_f32 v[8:9], v[8:9], v[100:101], v[18:19]
	v_add_u32_e32 v14, 0x8000, v14
	v_cvt_pk_bf16_f32 v16, v8, v9
	global_store_dword v14, v16, s[8:9]
	v_lshlrev_b32_e32 v18, 16, v51
	v_and_b32_e32 v19, 0xffff0000, v51
	v_pk_fma_f32 v[8:9], v[8:9], v[102:103], v[18:19]
	v_add_u32_e32 v14, 0x8000, v14
	v_cvt_pk_bf16_f32 v16, v8, v9
	global_store_dword v14, v16, s[8:9]
	v_lshlrev_b32_e32 v18, 16, v52
	v_and_b32_e32 v19, 0xffff0000, v52
	v_pk_fma_f32 v[8:9], v[8:9], v[104:105], v[18:19]
	v_add_u32_e32 v14, 0x8000, v14
	v_cvt_pk_bf16_f32 v16, v8, v9
	global_store_dword v14, v16, s[8:9]
	v_lshlrev_b32_e32 v18, 16, v53
	v_and_b32_e32 v19, 0xffff0000, v53
	v_pk_fma_f32 v[8:9], v[8:9], v[106:107], v[18:19]
	v_add_u32_e32 v14, 0x8000, v14
	v_cvt_pk_bf16_f32 v16, v8, v9
	global_store_dword v14, v16, s[8:9]
	v_lshlrev_b32_e32 v18, 16, v54
	v_and_b32_e32 v19, 0xffff0000, v54
	v_pk_fma_f32 v[8:9], v[8:9], v[108:109], v[18:19]
	v_add_u32_e32 v14, 0x8000, v14
	v_cvt_pk_bf16_f32 v16, v8, v9
	global_store_dword v14, v16, s[8:9]
	v_lshlrev_b32_e32 v18, 16, v55
	v_and_b32_e32 v19, 0xffff0000, v55
	v_pk_fma_f32 v[8:9], v[8:9], v[110:111], v[18:19]
	v_add_u32_e32 v14, 0x8000, v14
	v_cvt_pk_bf16_f32 v16, v8, v9
	global_store_dword v14, v16, s[8:9]
	v_lshlrev_b32_e32 v18, 16, v56
	v_and_b32_e32 v19, 0xffff0000, v56
	v_pk_fma_f32 v[8:9], v[8:9], v[112:113], v[18:19]
	v_add_u32_e32 v14, 0x8000, v14
	v_cvt_pk_bf16_f32 v16, v8, v9
	global_store_dword v14, v16, s[8:9]
	v_lshlrev_b32_e32 v18, 16, v57
	v_and_b32_e32 v19, 0xffff0000, v57
	v_pk_fma_f32 v[8:9], v[8:9], v[114:115], v[18:19]
	v_add_u32_e32 v14, 0x8000, v14
	v_cvt_pk_bf16_f32 v16, v8, v9
	global_store_dword v14, v16, s[8:9]
	v_lshlrev_b32_e32 v18, 16, v58
	v_and_b32_e32 v19, 0xffff0000, v58
	v_pk_fma_f32 v[8:9], v[8:9], v[116:117], v[18:19]
	v_add_u32_e32 v14, 0x8000, v14
	v_cvt_pk_bf16_f32 v16, v8, v9
	global_store_dword v14, v16, s[8:9]
	v_lshlrev_b32_e32 v18, 16, v59
	v_and_b32_e32 v19, 0xffff0000, v59
	v_pk_fma_f32 v[8:9], v[8:9], v[118:119], v[18:19]
	v_add_u32_e32 v14, 0x8000, v14
	v_cvt_pk_bf16_f32 v16, v8, v9
	global_store_dword v14, v16, s[8:9]
	v_lshlrev_b32_e32 v18, 16, v60
	v_and_b32_e32 v19, 0xffff0000, v60
	v_pk_fma_f32 v[8:9], v[8:9], v[120:121], v[18:19]
	v_add_u32_e32 v14, 0x8000, v14
	v_cvt_pk_bf16_f32 v16, v8, v9
	global_store_dword v14, v16, s[8:9]
	v_lshlrev_b32_e32 v18, 16, v61
	v_and_b32_e32 v19, 0xffff0000, v61
	v_pk_fma_f32 v[8:9], v[8:9], v[122:123], v[18:19]
	v_add_u32_e32 v14, 0x8000, v14
	v_cvt_pk_bf16_f32 v16, v8, v9
	global_store_dword v14, v16, s[8:9]
	v_lshlrev_b32_e32 v18, 16, v62
	v_and_b32_e32 v19, 0xffff0000, v62
	v_pk_fma_f32 v[8:9], v[8:9], v[124:125], v[18:19]
	v_add_u32_e32 v14, 0x8000, v14
	v_cvt_pk_bf16_f32 v16, v8, v9
	global_store_dword v14, v16, s[8:9]
	v_lshlrev_b32_e32 v18, 16, v63
	v_and_b32_e32 v19, 0xffff0000, v63
	v_pk_fma_f32 v[8:9], v[8:9], v[126:127], v[18:19]
	v_add_u32_e32 v14, 0x8000, v14
	v_add_u32_e32 v10, s1, v10
	s_mov_b32 s0, 0xffff
	v_cmp_lt_i32_e32 vcc, s0, v10
	s_or_b64 s[6:7], vcc, s[6:7]
	v_add_u16_e32 v11, s1, v11
	s_andn2_b64 exec, exec, s[6:7]
	s_cbranch_execnz .LBB0_621
